# P6 loop: 32-term row-sum and 16-op row-max chains split into two interleaved independent chains
# baseline (speedup 1.0000x reference)
; __device__ __forceinline__ void finishSM(f32x16& p0, f32x16& p1, float alpha, float& l_reg, bf16x8& pa0, bf16x8& pa1, bf16x8& pa2, bf16x8& pa3) {
; #pragma unroll
;     for (int r = 0; r < 16; ++r) p1[r] = __builtin_amdgcn_exp2f(p1[r]);
;     float ps = 0;
; #pragma unroll
;     for (int r = 0; r < 16; ++r) ps += p0[r];
; #pragma unroll
;     for (int r = 0; r < 16; ++r) ps += p1[r];
;     { auto rr = __builtin_amdgcn_permlane32_swap(__float_as_uint(ps), __float_as_uint(ps), false, false);
;       ps = __uint_as_float(rr[0]) + __uint_as_float(rr[1]); }
;     l_reg = l_reg * alpha + ps;
;     PK4(p0, 0, pa0); PK4(p0, 8, pa1); PK4(p1, 0, pa2); PK4(p1, 8, pa3);
.LBB0_1334:
	s_andn2_b64 s[6:7], exec, s[84:85]
	s_andn2_b64 vcc, exec, s[84:85]
	s_cbranch_vccnz .LBB0_1336
	v_add_f32_e32 v2, v128, v129
	v_add_f32_e32 v3, v130, v131
	v_add_f32_e32 v2, v132, v2
	v_add_f32_e32 v3, v133, v3
	v_add_f32_e32 v2, v134, v2
	v_add_f32_e32 v3, v135, v3
	v_add_f32_e32 v2, v136, v2
	v_add_f32_e32 v3, v137, v3
	v_add_f32_e32 v2, v138, v2
	v_add_f32_e32 v3, v139, v3
	v_exp_f32_e32 v96, v96
	v_add_f32_e32 v2, v140, v2
	v_exp_f32_e32 v97, v97
	v_add_f32_e32 v3, v141, v3
	v_exp_f32_e32 v98, v98
	v_add_f32_e32 v2, v142, v2
	v_exp_f32_e32 v99, v99
	v_add_f32_e32 v3, v143, v3
	v_exp_f32_e32 v100, v100
	v_add_f32_e32 v2, v96, v2
	v_exp_f32_e32 v101, v101
	v_add_f32_e32 v3, v97, v3
	v_exp_f32_e32 v102, v102
	v_add_f32_e32 v2, v98, v2
	v_exp_f32_e32 v103, v103
	v_add_f32_e32 v3, v99, v3
	v_exp_f32_e32 v104, v104
	v_add_f32_e32 v2, v100, v2
	v_exp_f32_e32 v105, v105
	v_add_f32_e32 v3, v101, v3
	v_exp_f32_e32 v106, v106
	v_add_f32_e32 v2, v102, v2
	v_exp_f32_e32 v107, v107
	v_add_f32_e32 v3, v103, v3
	v_exp_f32_e32 v108, v108
	v_add_f32_e32 v2, v104, v2
	v_exp_f32_e32 v109, v109
	v_add_f32_e32 v3, v105, v3
	v_exp_f32_e32 v110, v110
	v_add_f32_e32 v2, v106, v2
	v_exp_f32_e32 v111, v111
	v_add_f32_e32 v3, v107, v3
	v_add_f32_e32 v2, v108, v2
	v_add_f32_e32 v3, v109, v3
	v_add_f32_e32 v2, v110, v2
	v_add_f32_e32 v3, v111, v3
	v_add_f32_e32 v2, v2, v3
	v_mov_b32_e32 v3, v2
	s_nop 1
	v_permlane32_swap_b32_e32 v2, v3
	v_add_f32_e32 v2, v2, v3
	v_fma_f32 v227, v243, v227, v2
	v_cvt_pk_bf16_f32 v192, v128, v129
	v_cvt_pk_bf16_f32 v193, v130, v131
	v_cvt_pk_bf16_f32 v194, v132, v133
	v_cvt_pk_bf16_f32 v195, v134, v135
	v_cvt_pk_bf16_f32 v196, v136, v137
	v_cvt_pk_bf16_f32 v197, v138, v139
	v_cvt_pk_bf16_f32 v198, v140, v141
	v_cvt_pk_bf16_f32 v199, v142, v143
	v_cvt_pk_bf16_f32 v200, v96, v97
	v_cvt_pk_bf16_f32 v201, v98, v99
	v_cvt_pk_bf16_f32 v202, v100, v101
	v_cvt_pk_bf16_f32 v203, v102, v103
	v_cvt_pk_bf16_f32 v204, v104, v105
	v_cvt_pk_bf16_f32 v205, v106, v107
	v_cvt_pk_bf16_f32 v206, v108, v109
	v_cvt_pk_bf16_f32 v207, v110, v111
	s_nop 0
	v_permlane32_swap_b32_e32 v192, v194
	v_permlane32_swap_b32_e32 v193, v195
	v_permlane32_swap_b32_e32 v196, v198
	v_permlane32_swap_b32_e32 v197, v199
	v_permlane32_swap_b32_e32 v200, v202
	v_permlane32_swap_b32_e32 v201, v203
	v_permlane32_swap_b32_e32 v204, v206
	v_permlane32_swap_b32_e32 v205, v207

; __device__ __forceinline__ void partialSM(f32x16& p0, f32x16& p1, float& m_reg, float& mn, float& alpha) {
;     float pmax = p0[0];
; #pragma unroll
;     for (int r = 1; r < 16; ++r) pmax = fmaxf(pmax, p0[r]);
; #pragma unroll
;     for (int r = 0; r < 16; ++r) pmax = fmaxf(pmax, p1[r]);
;     { auto rr = __builtin_amdgcn_permlane32_swap(__float_as_uint(pmax), __float_as_uint(pmax), false, false);
;       pmax = fmaxf(__uint_as_float(rr[0]), __uint_as_float(rr[1])); }
;     constexpr float C2 = 1.4426950408889634f * SM_SCALE;
;     if (__builtin_expect(__all((pmax - m_reg) * SM_SCALE <= THR), 1)) { mn = m_reg; alpha = 1.f; }
;     else { mn = fmaxf(m_reg, pmax); alpha = __builtin_amdgcn_exp2f((m_reg - mn) * C2); m_reg = mn; }
;     const float mnL = -mn * C2;
; #pragma unroll
;     for (int r = 0; r < 16; ++r) p0[r] = fmaf(p0[r], C2, mnL);
; #pragma unroll
;     for (int r = 0; r < 16; ++r) p1[r] = fmaf(p1[r], C2, mnL);
; #pragma unroll
;     for (int r = 0; r < 16; ++r) p0[r] = __builtin_amdgcn_exp2f(p0[r]);
.LBB0_1373:
	v_cmp_eq_u32_e64 s[6:7], 0, v0
	v_max_f32_e32 v0, v112, v113
	v_max_f32_e32 v14, v80, v81
	v_max3_f32 v0, v0, v114, v115
	v_max3_f32 v14, v14, v82, v83
	v_max3_f32 v0, v0, v116, v117
	v_max3_f32 v14, v14, v84, v85
	v_max3_f32 v0, v0, v118, v119
	v_max3_f32 v14, v14, v86, v87
	v_max3_f32 v0, v0, v120, v121
	v_max3_f32 v14, v14, v88, v89
	v_max3_f32 v0, v0, v122, v123
	v_max3_f32 v14, v14, v90, v91
	v_max3_f32 v0, v0, v124, v125
	v_max3_f32 v14, v14, v92, v93
	v_max3_f32 v0, v0, v126, v127
	v_max3_f32 v14, v14, v94, v95
	v_max_f32_e32 v0, v0, v14
	v_cndmask_b32_e64 v0, v0, v216, s[6:7]
	v_mov_b32_e32 v14, v0
	s_nop 1
	v_permlane32_swap_b32_e32 v0, v14
	v_max_f32_e32 v0, v0, v14
	v_sub_f32_e32 v14, v0, v228
	v_mul_f32_e32 v14, 0x3db504f3, v14
	v_cmp_ge_f32_e32 vcc, s93, v14
	v_max_f32_e32 v0, v228, v0
	v_sub_f32_e32 v14, v228, v0
	v_mul_f32_e32 v14, 0x3e0293ee, v14
	s_cmp_eq_u64 vcc, exec
	v_exp_f32_e32 v14, v14
	s_cselect_b64 vcc, -1, 0
	v_cndmask_b32_e32 v228, v0, v228, vcc
	v_mul_f32_e32 v0, 0xbe0293ee, v228
	v_cndmask_b32_e64 v14, v14, 1.0, vcc
	v_cndmask_b32_e64 v0, v0, v216, s[6:7]
	v_fmamk_f32 v112, v112, 0x3e0293ee, v0
	v_fmamk_f32 v113, v113, 0x3e0293ee, v0
	v_fmamk_f32 v114, v114, 0x3e0293ee, v0
	v_fmamk_f32 v115, v115, 0x3e0293ee, v0
	v_fmamk_f32 v116, v116, 0x3e0293ee, v0
	v_fmamk_f32 v117, v117, 0x3e0293ee, v0
	v_fmamk_f32 v118, v118, 0x3e0293ee, v0
	v_fmamk_f32 v119, v119, 0x3e0293ee, v0
	v_fmamk_f32 v120, v120, 0x3e0293ee, v0
	v_fmamk_f32 v121, v121, 0x3e0293ee, v0
	v_fmamk_f32 v122, v122, 0x3e0293ee, v0
	v_fmamk_f32 v123, v123, 0x3e0293ee, v0
	v_fmamk_f32 v124, v124, 0x3e0293ee, v0
	v_fmamk_f32 v125, v125, 0x3e0293ee, v0
	v_fmamk_f32 v126, v126, 0x3e0293ee, v0
	v_fmamk_f32 v127, v127, 0x3e0293ee, v0
	v_exp_f32_e32 v112, v112
	v_exp_f32_e32 v113, v113
	v_exp_f32_e32 v114, v114
	v_exp_f32_e32 v115, v115
	v_exp_f32_e32 v116, v116
	v_exp_f32_e32 v117, v117
	v_exp_f32_e32 v118, v118
	v_exp_f32_e32 v119, v119
	v_exp_f32_e32 v120, v120
	v_exp_f32_e32 v121, v121
	v_exp_f32_e32 v122, v122
	v_exp_f32_e32 v123, v123
	v_exp_f32_e32 v124, v124
	v_exp_f32_e32 v125, v125
	v_exp_f32_e32 v126, v126
	v_exp_f32_e32 v127, v127
	v_pk_fma_f32 v[94:95], v[94:95], s[72:73], v[0:1] op_sel_hi:[1,0,0]
	v_pk_fma_f32 v[92:93], v[92:93], s[72:73], v[0:1] op_sel_hi:[1,0,0]
	v_pk_fma_f32 v[90:91], v[90:91], s[72:73], v[0:1] op_sel_hi:[1,0,0]
	v_pk_fma_f32 v[88:89], v[88:89], s[72:73], v[0:1] op_sel_hi:[1,0,0]
	v_pk_fma_f32 v[86:87], v[86:87], s[72:73], v[0:1] op_sel_hi:[1,0,0]
	v_pk_fma_f32 v[84:85], v[84:85], s[72:73], v[0:1] op_sel_hi:[1,0,0]
	v_pk_fma_f32 v[82:83], v[82:83], s[72:73], v[0:1] op_sel_hi:[1,0,0]
	v_pk_fma_f32 v[80:81], v[80:81], s[72:73], v[0:1] op_sel_hi:[1,0,0]

; __device__ __forceinline__ void finishSM(f32x16& p0, f32x16& p1, float alpha, float& l_reg, bf16x8& pa0, bf16x8& pa1, bf16x8& pa2, bf16x8& pa3) {
; #pragma unroll
;     for (int r = 0; r < 16; ++r) p1[r] = __builtin_amdgcn_exp2f(p1[r]);
;     float ps = 0;
; #pragma unroll
;     for (int r = 0; r < 16; ++r) ps += p0[r];
; #pragma unroll
;     for (int r = 0; r < 16; ++r) ps += p1[r];
;     { auto rr = __builtin_amdgcn_permlane32_swap(__float_as_uint(ps), __float_as_uint(ps), false, false);
;       ps = __uint_as_float(rr[0]) + __uint_as_float(rr[1]); }
;     l_reg = l_reg * alpha + ps;
;     PK4(p0, 0, pa0); PK4(p0, 8, pa1); PK4(p1, 0, pa2); PK4(p1, 8, pa3);
.LBB0_1384:
	s_and_b64 vcc, exec, s[4:5]
	s_cbranch_vccnz .LBB0_1386
	v_add_f32_e32 v15, v112, v113
	v_add_f32_e32 v2, v114, v115
	v_add_f32_e32 v15, v116, v15
	v_add_f32_e32 v2, v117, v2
	v_add_f32_e32 v15, v118, v15
	v_add_f32_e32 v2, v119, v2
	v_add_f32_e32 v15, v120, v15
	v_add_f32_e32 v2, v121, v2
	v_add_f32_e32 v15, v122, v15
	v_add_f32_e32 v2, v123, v2
	v_exp_f32_e32 v80, v80
	v_add_f32_e32 v15, v124, v15
	v_exp_f32_e32 v81, v81
	v_add_f32_e32 v2, v125, v2
	v_exp_f32_e32 v82, v82
	v_add_f32_e32 v15, v126, v15
	v_exp_f32_e32 v83, v83
	v_add_f32_e32 v2, v127, v2
	v_exp_f32_e32 v84, v84
	v_add_f32_e32 v15, v80, v15
	v_exp_f32_e32 v85, v85
	v_add_f32_e32 v2, v81, v2
	v_exp_f32_e32 v86, v86
	v_add_f32_e32 v15, v82, v15
	v_exp_f32_e32 v87, v87
	v_add_f32_e32 v2, v83, v2
	v_exp_f32_e32 v88, v88
	v_add_f32_e32 v15, v84, v15
	v_exp_f32_e32 v89, v89
	v_add_f32_e32 v2, v85, v2
	v_exp_f32_e32 v90, v90
	v_add_f32_e32 v15, v86, v15
	v_exp_f32_e32 v91, v91
	v_add_f32_e32 v2, v87, v2
	v_exp_f32_e32 v92, v92
	v_add_f32_e32 v15, v88, v15
	v_exp_f32_e32 v93, v93
	v_add_f32_e32 v2, v89, v2
	v_exp_f32_e32 v94, v94
	v_add_f32_e32 v15, v90, v15
	v_exp_f32_e32 v95, v95
	v_add_f32_e32 v2, v91, v2
	v_add_f32_e32 v15, v92, v15
	v_add_f32_e32 v2, v93, v2
	v_add_f32_e32 v15, v94, v15
	v_add_f32_e32 v2, v95, v2
	v_add_f32_e32 v15, v15, v2
	v_mov_b32_e32 v144, v15
	s_nop 1
	v_permlane32_swap_b32_e32 v15, v144
	v_add_f32_e32 v15, v15, v144
	v_fma_f32 v227, v227, v14, v15
	v_cvt_pk_bf16_f32 v192, v112, v113
	v_cvt_pk_bf16_f32 v193, v114, v115
	v_cvt_pk_bf16_f32 v194, v116, v117
	v_cvt_pk_bf16_f32 v195, v118, v119
	v_cvt_pk_bf16_f32 v196, v120, v121
	v_cvt_pk_bf16_f32 v197, v122, v123
	v_cvt_pk_bf16_f32 v198, v124, v125
	v_cvt_pk_bf16_f32 v199, v126, v127
	v_cvt_pk_bf16_f32 v200, v80, v81
	v_cvt_pk_bf16_f32 v201, v82, v83
	v_cvt_pk_bf16_f32 v202, v84, v85
	v_cvt_pk_bf16_f32 v203, v86, v87
	v_cvt_pk_bf16_f32 v204, v88, v89
	v_cvt_pk_bf16_f32 v205, v90, v91
	v_cvt_pk_bf16_f32 v206, v92, v93
	v_cvt_pk_bf16_f32 v207, v94, v95
	s_nop 0
	v_permlane32_swap_b32_e32 v192, v194
	v_permlane32_swap_b32_e32 v193, v195
	v_permlane32_swap_b32_e32 v196, v198
	v_permlane32_swap_b32_e32 v197, v199
	v_permlane32_swap_b32_e32 v200, v202
	v_permlane32_swap_b32_e32 v201, v203
	v_permlane32_swap_b32_e32 v204, v206
	v_permlane32_swap_b32_e32 v205, v207

; __device__ __forceinline__ void partialSM(f32x16& p0, f32x16& p1, float& m_reg, float& mn, float& alpha) {
;     float pmax = p0[0];
; #pragma unroll
;     for (int r = 1; r < 16; ++r) pmax = fmaxf(pmax, p0[r]);
; #pragma unroll
;     for (int r = 0; r < 16; ++r) pmax = fmaxf(pmax, p1[r]);
;     { auto rr = __builtin_amdgcn_permlane32_swap(__float_as_uint(pmax), __float_as_uint(pmax), false, false);
;       pmax = fmaxf(__uint_as_float(rr[0]), __uint_as_float(rr[1])); }
;     constexpr float C2 = 1.4426950408889634f * SM_SCALE;
;     if (__builtin_expect(__all((pmax - m_reg) * SM_SCALE <= THR), 1)) { mn = m_reg; alpha = 1.f; }
;     else { mn = fmaxf(m_reg, pmax); alpha = __builtin_amdgcn_exp2f((m_reg - mn) * C2); m_reg = mn; }
;     const float mnL = -mn * C2;
; #pragma unroll
;     for (int r = 0; r < 16; ++r) p0[r] = fmaf(p0[r], C2, mnL);
; #pragma unroll
;     for (int r = 0; r < 16; ++r) p1[r] = fmaf(p1[r], C2, mnL);
; #pragma unroll
;     for (int r = 0; r < 16; ++r) p0[r] = __builtin_amdgcn_exp2f(p0[r]);
.LBB0_1425:
	v_cmp_eq_u32_e64 s[4:5], 0, v0
	v_max_f32_e32 v0, v128, v129
	v_max_f32_e32 v14, v96, v97
	v_max3_f32 v0, v0, v130, v131
	v_max3_f32 v14, v14, v98, v99
	v_max3_f32 v0, v0, v132, v133
	v_max3_f32 v14, v14, v100, v101
	v_max3_f32 v0, v0, v134, v135
	v_max3_f32 v14, v14, v102, v103
	v_max3_f32 v0, v0, v136, v137
	v_max3_f32 v14, v14, v104, v105
	v_max3_f32 v0, v0, v138, v139
	v_max3_f32 v14, v14, v106, v107
	v_max3_f32 v0, v0, v140, v141
	v_max3_f32 v14, v14, v108, v109
	v_max3_f32 v0, v0, v142, v143
	v_max3_f32 v14, v14, v110, v111
	v_max_f32_e32 v0, v0, v14
	v_cndmask_b32_e64 v0, v0, v216, s[4:5]
	v_mov_b32_e32 v14, v0
	s_nop 1
	v_permlane32_swap_b32_e32 v0, v14
	v_max_f32_e32 v0, v0, v14
	v_sub_f32_e32 v14, v0, v228
	v_mul_f32_e32 v14, 0x3db504f3, v14
	v_cmp_ge_f32_e32 vcc, s93, v14
	v_max_f32_e32 v0, v228, v0
	v_sub_f32_e32 v14, v228, v0
	v_mul_f32_e32 v14, 0x3e0293ee, v14
	s_cmp_eq_u64 vcc, exec
	v_exp_f32_e32 v14, v14
	s_cselect_b64 vcc, -1, 0
	v_cndmask_b32_e32 v228, v0, v228, vcc
	v_mul_f32_e32 v0, 0xbe0293ee, v228
	v_cndmask_b32_e64 v243, v14, 1.0, vcc
	v_cndmask_b32_e64 v0, v0, v216, s[4:5]
	v_fmamk_f32 v128, v128, 0x3e0293ee, v0
	v_fmamk_f32 v129, v129, 0x3e0293ee, v0
	v_fmamk_f32 v130, v130, 0x3e0293ee, v0
	v_fmamk_f32 v131, v131, 0x3e0293ee, v0
	v_fmamk_f32 v132, v132, 0x3e0293ee, v0
	v_fmamk_f32 v133, v133, 0x3e0293ee, v0
	v_fmamk_f32 v134, v134, 0x3e0293ee, v0
	v_fmamk_f32 v135, v135, 0x3e0293ee, v0
	v_fmamk_f32 v136, v136, 0x3e0293ee, v0
	v_fmamk_f32 v137, v137, 0x3e0293ee, v0
	v_fmamk_f32 v138, v138, 0x3e0293ee, v0
	v_fmamk_f32 v139, v139, 0x3e0293ee, v0
	v_fmamk_f32 v140, v140, 0x3e0293ee, v0
	v_fmamk_f32 v141, v141, 0x3e0293ee, v0
	v_fmamk_f32 v142, v142, 0x3e0293ee, v0
	v_fmamk_f32 v143, v143, 0x3e0293ee, v0
	v_exp_f32_e32 v128, v128
	v_exp_f32_e32 v129, v129
	v_exp_f32_e32 v130, v130
	v_exp_f32_e32 v131, v131
	v_exp_f32_e32 v132, v132
	v_exp_f32_e32 v133, v133
	v_exp_f32_e32 v134, v134
	v_exp_f32_e32 v135, v135
	v_exp_f32_e32 v136, v136
	v_exp_f32_e32 v137, v137
	v_exp_f32_e32 v138, v138
	v_exp_f32_e32 v139, v139
	v_exp_f32_e32 v140, v140
	v_exp_f32_e32 v141, v141
	v_exp_f32_e32 v142, v142
	v_exp_f32_e32 v143, v143
	v_pk_fma_f32 v[110:111], v[110:111], s[72:73], v[0:1] op_sel_hi:[1,0,0]
	v_pk_fma_f32 v[108:109], v[108:109], s[72:73], v[0:1] op_sel_hi:[1,0,0]
	v_pk_fma_f32 v[106:107], v[106:107], s[72:73], v[0:1] op_sel_hi:[1,0,0]
	v_pk_fma_f32 v[104:105], v[104:105], s[72:73], v[0:1] op_sel_hi:[1,0,0]
	v_pk_fma_f32 v[102:103], v[102:103], s[72:73], v[0:1] op_sel_hi:[1,0,0]
	v_pk_fma_f32 v[100:101], v[100:101], s[72:73], v[0:1] op_sel_hi:[1,0,0]
	v_pk_fma_f32 v[98:99], v[98:99], s[72:73], v[0:1] op_sel_hi:[1,0,0]
	v_pk_fma_f32 v[96:97], v[96:97], s[72:73], v[0:1] op_sel_hi:[1,0,0]
